# P2 tail: last 80 latent attention units handed out as 160 half units (waves 0-3 compute 128 queries, waves 4-7 stage only) + hand-written mixer-B items
# speedup vs baseline: 1.0228x; 1.0228x over previous
.LBB0_704:
	s_or_b64 exec, exec, s[2:3]
	s_waitcnt lgkmcnt(0)
	s_barrier
	ds_read_b32 v1, v214
	s_mov_b64 s[2:3], -1
	s_waitcnt lgkmcnt(0)
	v_readfirstlane_b32 s7, v1
	s_mov_b32 vcc_hi, 0
	s_cmpk_lt_u32 s7, 0x200
	s_cbranch_scc1 .Lqh_done
	s_cmpk_lt_u32 s7, 0x2a0
	s_cbranch_scc1 .Lqh_half
	s_add_i32 s7, s7, 0xffffffb0
	s_branch .Lqh_done
.Lqh_half:
	s_add_i32 vcc_lo, s7, 0xfffffe00
	s_and_b32 vcc_hi, vcc_lo, 1
	s_add_i32 vcc_hi, vcc_hi, 1
	s_lshr_b32 vcc_lo, vcc_lo, 1
	s_add_i32 s7, vcc_lo, 0x200
.Lqh_done:
	v_writelane_b32 v255, vcc_hi, 55
	s_cmp_ge_i32 s7, s6
	s_cbranch_scc1 .LBB0_699
	v_ashrrev_i32_e32 v218, 8, v212
	v_bfe_u32 v220, v212, 6, 2
	v_and_b32_e32 v219, 15, v212
	v_lshrrev_b32_e32 v223, 4, v212
	v_bfe_u32 v221, v212, 4, 2
	s_cmpk_gt_i32 s7, 0x4f
	s_cbranch_scc0 .LBB0_912
	s_cmpk_gt_u32 s7, 0x24f
	s_cbranch_scc0 .LBB0_876
	s_add_i32 s9, s7, 0xfffffdb0
	s_cmp_ge_i32 s9, s94
	s_cbranch_scc0 .LBB0_836
	s_sub_i32 s10, s9, s94
	s_cmp_ge_i32 s10, s53
	s_cbranch_scc0 .LBB0_723
	s_sub_i32 s11, s10, s53
	v_readlane_b32 s2, v255, 39
	s_cmp_ge_i32 s11, s2
	s_mov_b64 s[2:3], -1
	s_cbranch_scc0 .LBB0_717
	v_readlane_b32 s2, v255, 39
	s_sub_i32 s4, s11, s2
	s_lshl_b32 s4, s4, 7
	s_movk_i32 s5, 0xff
	s_cmp_lt_i32 s4, s68
	s_cselect_b32 s5, 0x7ff, s5
	v_lshrrev_b32_e32 v1, 5, v212
	v_and_b32_e32 v2, 31, v212
	v_lshlrev_b32_e32 v9, 5, v2
	v_lshlrev_b32_e32 v2, 4, v2
	v_lshl_add_u32 v3, v1, 3, s4
	v_and_b32_e32 v4, s5, v3
	v_cmp_ne_u32_e64 s[14:15], 0, v4
	v_add_u32_e32 v6, 7, v4
	v_cmp_ne_u32_e64 s[4:5], s5, v6
	v_mul_u32_u24_e32 v8, 0x600, v3
	v_add_u32_e32 v8, v8, v2
	v_lshlrev_b32_e32 v10, 11, v3
	v_add_u32_e32 v10, v10, v2
	v_readlane_b32 s2, v255, 10
	v_readlane_b32 s3, v255, 11
	v_readlane_b32 s12, v255, 41
	v_readlane_b32 s13, v255, 42
	s_nop 4
	global_load_dwordx4 v[20:23], v8, s[2:3] offset:-1536
	global_load_dwordx4 v[24:27], v8, s[2:3] offset:-512
	global_load_dwordx4 v[28:31], v8, s[2:3]
	global_load_dwordx4 v[32:35], v8, s[2:3] offset:1024
	global_load_dwordx4 v[100:103], v8, s[2:3] offset:512
	v_add_u32_e32 v8, 0x600, v8
	global_load_dwordx4 v[36:39], v8, s[2:3]
	global_load_dwordx4 v[40:43], v8, s[2:3] offset:1024
	global_load_dwordx4 v[104:107], v8, s[2:3] offset:512
	v_add_u32_e32 v8, 0x600, v8
	global_load_dwordx4 v[44:47], v8, s[2:3]
	global_load_dwordx4 v[48:51], v8, s[2:3] offset:1024
	global_load_dwordx4 v[108:111], v8, s[2:3] offset:512
	v_add_u32_e32 v8, 0x600, v8
	global_load_dwordx4 v[52:55], v8, s[2:3]
	global_load_dwordx4 v[56:59], v8, s[2:3] offset:1024
	global_load_dwordx4 v[112:115], v8, s[2:3] offset:512
	v_add_u32_e32 v8, 0x600, v8
	global_load_dwordx4 v[60:63], v8, s[2:3]
	global_load_dwordx4 v[64:67], v8, s[2:3] offset:1024
	global_load_dwordx4 v[116:119], v8, s[2:3] offset:512
	v_add_u32_e32 v8, 0x600, v8
	global_load_dwordx4 v[68:71], v8, s[2:3]
	global_load_dwordx4 v[72:75], v8, s[2:3] offset:1024
	global_load_dwordx4 v[120:123], v8, s[2:3] offset:512
	v_add_u32_e32 v8, 0x600, v8
	global_load_dwordx4 v[76:79], v8, s[2:3]
	global_load_dwordx4 v[80:83], v8, s[2:3] offset:1024
	global_load_dwordx4 v[124:127], v8, s[2:3] offset:512
	v_add_u32_e32 v8, 0x600, v8
	global_load_dwordx4 v[84:87], v8, s[2:3]
	global_load_dwordx4 v[88:91], v8, s[2:3] offset:1024
	global_load_dwordx4 v[128:131], v8, s[2:3] offset:512
	v_add_u32_e32 v8, 0x600, v8
	global_load_dwordx4 v[92:95], v8, s[2:3]
	global_load_dwordx4 v[96:99], v8, s[2:3] offset:1024
	global_load_dwordx4 v[132:135], v9, s[12:13] offset:0
	global_load_dwordx4 v[136:139], v9, s[12:13] offset:16
	global_load_dwordx4 v[140:143], v9, s[12:13] offset:1024
	global_load_dwordx4 v[144:147], v9, s[12:13] offset:1040
	global_load_dwordx4 v[148:151], v9, s[12:13] offset:2048
	global_load_dwordx4 v[152:155], v9, s[12:13] offset:2064
	s_waitcnt vmcnt(0)
	v_cvt_f32_f16_e32 v160, v20
	v_cvt_f32_f16_sdwa v161, v20 dst_sel:DWORD dst_unused:UNUSED_PAD src0_sel:WORD_1
	v_cvt_f32_f16_e32 v162, v21
	v_cvt_f32_f16_sdwa v163, v21 dst_sel:DWORD dst_unused:UNUSED_PAD src0_sel:WORD_1
	v_cvt_f32_f16_e32 v164, v22
	v_cvt_f32_f16_sdwa v165, v22 dst_sel:DWORD dst_unused:UNUSED_PAD src0_sel:WORD_1
	v_cvt_f32_f16_e32 v166, v23
	v_cvt_f32_f16_sdwa v167, v23 dst_sel:DWORD dst_unused:UNUSED_PAD src0_sel:WORD_1
	v_cvt_f32_f16_e32 v168, v24
	v_cvt_f32_f16_sdwa v169, v24 dst_sel:DWORD dst_unused:UNUSED_PAD src0_sel:WORD_1
	v_cvt_f32_f16_e32 v170, v25
	v_cvt_f32_f16_sdwa v171, v25 dst_sel:DWORD dst_unused:UNUSED_PAD src0_sel:WORD_1
	v_cvt_f32_f16_e32 v172, v26
	v_cvt_f32_f16_sdwa v173, v26 dst_sel:DWORD dst_unused:UNUSED_PAD src0_sel:WORD_1
	v_cvt_f32_f16_e32 v174, v27
	v_cvt_f32_f16_sdwa v175, v27 dst_sel:DWORD dst_unused:UNUSED_PAD src0_sel:WORD_1
	v_pk_mul_f32 v[20:21], v[160:161], v[168:169]
	v_pk_mul_f32 v[22:23], v[162:163], v[170:171]
	v_pk_mul_f32 v[24:25], v[164:165], v[172:173]
	v_pk_mul_f32 v[26:27], v[166:167], v[174:175]
	v_cndmask_b32_e64 v20, 0, v20, s[14:15]
	v_cndmask_b32_e64 v21, 0, v21, s[14:15]
	v_cndmask_b32_e64 v22, 0, v22, s[14:15]
	v_cndmask_b32_e64 v23, 0, v23, s[14:15]
	v_cndmask_b32_e64 v24, 0, v24, s[14:15]
	v_cndmask_b32_e64 v25, 0, v25, s[14:15]
	v_cndmask_b32_e64 v26, 0, v26, s[14:15]
	v_cndmask_b32_e64 v27, 0, v27, s[14:15]
	v_cvt_f32_f16_e32 v160, v28
	v_cvt_f32_f16_sdwa v161, v28 dst_sel:DWORD dst_unused:UNUSED_PAD src0_sel:WORD_1
	v_cvt_f32_f16_e32 v162, v29
	v_cvt_f32_f16_sdwa v163, v29 dst_sel:DWORD dst_unused:UNUSED_PAD src0_sel:WORD_1
	v_cvt_f32_f16_e32 v164, v30
	v_cvt_f32_f16_sdwa v165, v30 dst_sel:DWORD dst_unused:UNUSED_PAD src0_sel:WORD_1
	v_cvt_f32_f16_e32 v166, v31
	v_cvt_f32_f16_sdwa v167, v31 dst_sel:DWORD dst_unused:UNUSED_PAD src0_sel:WORD_1
	v_cvt_f32_f16_e32 v168, v32
	v_cvt_f32_f16_sdwa v169, v32 dst_sel:DWORD dst_unused:UNUSED_PAD src0_sel:WORD_1
	v_cvt_f32_f16_e32 v170, v33
	v_cvt_f32_f16_sdwa v171, v33 dst_sel:DWORD dst_unused:UNUSED_PAD src0_sel:WORD_1
	v_cvt_f32_f16_e32 v172, v34
	v_cvt_f32_f16_sdwa v173, v34 dst_sel:DWORD dst_unused:UNUSED_PAD src0_sel:WORD_1
	v_cvt_f32_f16_e32 v174, v35
	v_cvt_f32_f16_sdwa v175, v35 dst_sel:DWORD dst_unused:UNUSED_PAD src0_sel:WORD_1
	v_pk_mul_f32 v[28:29], v[160:161], v[168:169]
	v_pk_mul_f32 v[30:31], v[162:163], v[170:171]
	v_pk_mul_f32 v[32:33], v[164:165], v[172:173]
	v_pk_mul_f32 v[34:35], v[166:167], v[174:175]
	v_cvt_f32_f16_e32 v160, v36
	v_cvt_f32_f16_sdwa v161, v36 dst_sel:DWORD dst_unused:UNUSED_PAD src0_sel:WORD_1
	v_cvt_f32_f16_e32 v162, v37
	v_cvt_f32_f16_sdwa v163, v37 dst_sel:DWORD dst_unused:UNUSED_PAD src0_sel:WORD_1
	v_cvt_f32_f16_e32 v164, v38
	v_cvt_f32_f16_sdwa v165, v38 dst_sel:DWORD dst_unused:UNUSED_PAD src0_sel:WORD_1
	v_cvt_f32_f16_e32 v166, v39
	v_cvt_f32_f16_sdwa v167, v39 dst_sel:DWORD dst_unused:UNUSED_PAD src0_sel:WORD_1
	v_cvt_f32_f16_e32 v168, v40
	v_cvt_f32_f16_sdwa v169, v40 dst_sel:DWORD dst_unused:UNUSED_PAD src0_sel:WORD_1
	v_cvt_f32_f16_e32 v170, v41
	v_cvt_f32_f16_sdwa v171, v41 dst_sel:DWORD dst_unused:UNUSED_PAD src0_sel:WORD_1
	v_cvt_f32_f16_e32 v172, v42
	v_cvt_f32_f16_sdwa v173, v42 dst_sel:DWORD dst_unused:UNUSED_PAD src0_sel:WORD_1
	v_cvt_f32_f16_e32 v174, v43
	v_cvt_f32_f16_sdwa v175, v43 dst_sel:DWORD dst_unused:UNUSED_PAD src0_sel:WORD_1
	v_pk_mul_f32 v[36:37], v[160:161], v[168:169]
	v_pk_mul_f32 v[38:39], v[162:163], v[170:171]
	v_pk_mul_f32 v[40:41], v[164:165], v[172:173]
	v_pk_mul_f32 v[42:43], v[166:167], v[174:175]
	v_cvt_f32_f16_e32 v160, v44
	v_cvt_f32_f16_sdwa v161, v44 dst_sel:DWORD dst_unused:UNUSED_PAD src0_sel:WORD_1
	v_cvt_f32_f16_e32 v162, v45
	v_cvt_f32_f16_sdwa v163, v45 dst_sel:DWORD dst_unused:UNUSED_PAD src0_sel:WORD_1
	v_cvt_f32_f16_e32 v164, v46
	v_cvt_f32_f16_sdwa v165, v46 dst_sel:DWORD dst_unused:UNUSED_PAD src0_sel:WORD_1
	v_cvt_f32_f16_e32 v166, v47
	v_cvt_f32_f16_sdwa v167, v47 dst_sel:DWORD dst_unused:UNUSED_PAD src0_sel:WORD_1
	v_cvt_f32_f16_e32 v168, v48
	v_cvt_f32_f16_sdwa v169, v48 dst_sel:DWORD dst_unused:UNUSED_PAD src0_sel:WORD_1
	v_cvt_f32_f16_e32 v170, v49
	v_cvt_f32_f16_sdwa v171, v49 dst_sel:DWORD dst_unused:UNUSED_PAD src0_sel:WORD_1
	v_cvt_f32_f16_e32 v172, v50
	v_cvt_f32_f16_sdwa v173, v50 dst_sel:DWORD dst_unused:UNUSED_PAD src0_sel:WORD_1
	v_cvt_f32_f16_e32 v174, v51
	v_cvt_f32_f16_sdwa v175, v51 dst_sel:DWORD dst_unused:UNUSED_PAD src0_sel:WORD_1
	v_pk_mul_f32 v[44:45], v[160:161], v[168:169]
	v_pk_mul_f32 v[46:47], v[162:163], v[170:171]
	v_pk_mul_f32 v[48:49], v[164:165], v[172:173]
	v_pk_mul_f32 v[50:51], v[166:167], v[174:175]
	v_cvt_f32_f16_e32 v160, v52
	v_cvt_f32_f16_sdwa v161, v52 dst_sel:DWORD dst_unused:UNUSED_PAD src0_sel:WORD_1
	v_cvt_f32_f16_e32 v162, v53
	v_cvt_f32_f16_sdwa v163, v53 dst_sel:DWORD dst_unused:UNUSED_PAD src0_sel:WORD_1
	v_cvt_f32_f16_e32 v164, v54
	v_cvt_f32_f16_sdwa v165, v54 dst_sel:DWORD dst_unused:UNUSED_PAD src0_sel:WORD_1
	v_cvt_f32_f16_e32 v166, v55
	v_cvt_f32_f16_sdwa v167, v55 dst_sel:DWORD dst_unused:UNUSED_PAD src0_sel:WORD_1
	v_cvt_f32_f16_e32 v168, v56
	v_cvt_f32_f16_sdwa v169, v56 dst_sel:DWORD dst_unused:UNUSED_PAD src0_sel:WORD_1
	v_cvt_f32_f16_e32 v170, v57
	v_cvt_f32_f16_sdwa v171, v57 dst_sel:DWORD dst_unused:UNUSED_PAD src0_sel:WORD_1
	v_cvt_f32_f16_e32 v172, v58
	v_cvt_f32_f16_sdwa v173, v58 dst_sel:DWORD dst_unused:UNUSED_PAD src0_sel:WORD_1
	v_cvt_f32_f16_e32 v174, v59
	v_cvt_f32_f16_sdwa v175, v59 dst_sel:DWORD dst_unused:UNUSED_PAD src0_sel:WORD_1
	v_pk_mul_f32 v[52:53], v[160:161], v[168:169]
	v_pk_mul_f32 v[54:55], v[162:163], v[170:171]
	v_pk_mul_f32 v[56:57], v[164:165], v[172:173]
	v_pk_mul_f32 v[58:59], v[166:167], v[174:175]
	v_cvt_f32_f16_e32 v160, v60
	v_cvt_f32_f16_sdwa v161, v60 dst_sel:DWORD dst_unused:UNUSED_PAD src0_sel:WORD_1
	v_cvt_f32_f16_e32 v162, v61
	v_cvt_f32_f16_sdwa v163, v61 dst_sel:DWORD dst_unused:UNUSED_PAD src0_sel:WORD_1
	v_cvt_f32_f16_e32 v164, v62
	v_cvt_f32_f16_sdwa v165, v62 dst_sel:DWORD dst_unused:UNUSED_PAD src0_sel:WORD_1
	v_cvt_f32_f16_e32 v166, v63
	v_cvt_f32_f16_sdwa v167, v63 dst_sel:DWORD dst_unused:UNUSED_PAD src0_sel:WORD_1
	v_cvt_f32_f16_e32 v168, v64
	v_cvt_f32_f16_sdwa v169, v64 dst_sel:DWORD dst_unused:UNUSED_PAD src0_sel:WORD_1
	v_cvt_f32_f16_e32 v170, v65
	v_cvt_f32_f16_sdwa v171, v65 dst_sel:DWORD dst_unused:UNUSED_PAD src0_sel:WORD_1
	v_cvt_f32_f16_e32 v172, v66
	v_cvt_f32_f16_sdwa v173, v66 dst_sel:DWORD dst_unused:UNUSED_PAD src0_sel:WORD_1
	v_cvt_f32_f16_e32 v174, v67
	v_cvt_f32_f16_sdwa v175, v67 dst_sel:DWORD dst_unused:UNUSED_PAD src0_sel:WORD_1
	v_pk_mul_f32 v[60:61], v[160:161], v[168:169]
	v_pk_mul_f32 v[62:63], v[162:163], v[170:171]
	v_pk_mul_f32 v[64:65], v[164:165], v[172:173]
	v_pk_mul_f32 v[66:67], v[166:167], v[174:175]
	v_cvt_f32_f16_e32 v160, v68
	v_cvt_f32_f16_sdwa v161, v68 dst_sel:DWORD dst_unused:UNUSED_PAD src0_sel:WORD_1
	v_cvt_f32_f16_e32 v162, v69
	v_cvt_f32_f16_sdwa v163, v69 dst_sel:DWORD dst_unused:UNUSED_PAD src0_sel:WORD_1
	v_cvt_f32_f16_e32 v164, v70
	v_cvt_f32_f16_sdwa v165, v70 dst_sel:DWORD dst_unused:UNUSED_PAD src0_sel:WORD_1
	v_cvt_f32_f16_e32 v166, v71
	v_cvt_f32_f16_sdwa v167, v71 dst_sel:DWORD dst_unused:UNUSED_PAD src0_sel:WORD_1
	v_cvt_f32_f16_e32 v168, v72
	v_cvt_f32_f16_sdwa v169, v72 dst_sel:DWORD dst_unused:UNUSED_PAD src0_sel:WORD_1
	v_cvt_f32_f16_e32 v170, v73
	v_cvt_f32_f16_sdwa v171, v73 dst_sel:DWORD dst_unused:UNUSED_PAD src0_sel:WORD_1
	v_cvt_f32_f16_e32 v172, v74
	v_cvt_f32_f16_sdwa v173, v74 dst_sel:DWORD dst_unused:UNUSED_PAD src0_sel:WORD_1
	v_cvt_f32_f16_e32 v174, v75
	v_cvt_f32_f16_sdwa v175, v75 dst_sel:DWORD dst_unused:UNUSED_PAD src0_sel:WORD_1
	v_pk_mul_f32 v[68:69], v[160:161], v[168:169]
	v_pk_mul_f32 v[70:71], v[162:163], v[170:171]
	v_pk_mul_f32 v[72:73], v[164:165], v[172:173]
	v_pk_mul_f32 v[74:75], v[166:167], v[174:175]
	v_cvt_f32_f16_e32 v160, v76
	v_cvt_f32_f16_sdwa v161, v76 dst_sel:DWORD dst_unused:UNUSED_PAD src0_sel:WORD_1
	v_cvt_f32_f16_e32 v162, v77
	v_cvt_f32_f16_sdwa v163, v77 dst_sel:DWORD dst_unused:UNUSED_PAD src0_sel:WORD_1
	v_cvt_f32_f16_e32 v164, v78
	v_cvt_f32_f16_sdwa v165, v78 dst_sel:DWORD dst_unused:UNUSED_PAD src0_sel:WORD_1
	v_cvt_f32_f16_e32 v166, v79
	v_cvt_f32_f16_sdwa v167, v79 dst_sel:DWORD dst_unused:UNUSED_PAD src0_sel:WORD_1
	v_cvt_f32_f16_e32 v168, v80
	v_cvt_f32_f16_sdwa v169, v80 dst_sel:DWORD dst_unused:UNUSED_PAD src0_sel:WORD_1
	v_cvt_f32_f16_e32 v170, v81
	v_cvt_f32_f16_sdwa v171, v81 dst_sel:DWORD dst_unused:UNUSED_PAD src0_sel:WORD_1
	v_cvt_f32_f16_e32 v172, v82
	v_cvt_f32_f16_sdwa v173, v82 dst_sel:DWORD dst_unused:UNUSED_PAD src0_sel:WORD_1
	v_cvt_f32_f16_e32 v174, v83
	v_cvt_f32_f16_sdwa v175, v83 dst_sel:DWORD dst_unused:UNUSED_PAD src0_sel:WORD_1
	v_pk_mul_f32 v[76:77], v[160:161], v[168:169]
	v_pk_mul_f32 v[78:79], v[162:163], v[170:171]
	v_pk_mul_f32 v[80:81], v[164:165], v[172:173]
	v_pk_mul_f32 v[82:83], v[166:167], v[174:175]
	v_cvt_f32_f16_e32 v160, v84
	v_cvt_f32_f16_sdwa v161, v84 dst_sel:DWORD dst_unused:UNUSED_PAD src0_sel:WORD_1
	v_cvt_f32_f16_e32 v162, v85
	v_cvt_f32_f16_sdwa v163, v85 dst_sel:DWORD dst_unused:UNUSED_PAD src0_sel:WORD_1
	v_cvt_f32_f16_e32 v164, v86
	v_cvt_f32_f16_sdwa v165, v86 dst_sel:DWORD dst_unused:UNUSED_PAD src0_sel:WORD_1
	v_cvt_f32_f16_e32 v166, v87
	v_cvt_f32_f16_sdwa v167, v87 dst_sel:DWORD dst_unused:UNUSED_PAD src0_sel:WORD_1
	v_cvt_f32_f16_e32 v168, v88
	v_cvt_f32_f16_sdwa v169, v88 dst_sel:DWORD dst_unused:UNUSED_PAD src0_sel:WORD_1
	v_cvt_f32_f16_e32 v170, v89
	v_cvt_f32_f16_sdwa v171, v89 dst_sel:DWORD dst_unused:UNUSED_PAD src0_sel:WORD_1
	v_cvt_f32_f16_e32 v172, v90
	v_cvt_f32_f16_sdwa v173, v90 dst_sel:DWORD dst_unused:UNUSED_PAD src0_sel:WORD_1
	v_cvt_f32_f16_e32 v174, v91
	v_cvt_f32_f16_sdwa v175, v91 dst_sel:DWORD dst_unused:UNUSED_PAD src0_sel:WORD_1
	v_pk_mul_f32 v[84:85], v[160:161], v[168:169]
	v_pk_mul_f32 v[86:87], v[162:163], v[170:171]
	v_pk_mul_f32 v[88:89], v[164:165], v[172:173]
	v_pk_mul_f32 v[90:91], v[166:167], v[174:175]
	v_cvt_f32_f16_e32 v160, v92
	v_cvt_f32_f16_sdwa v161, v92 dst_sel:DWORD dst_unused:UNUSED_PAD src0_sel:WORD_1
	v_cvt_f32_f16_e32 v162, v93
	v_cvt_f32_f16_sdwa v163, v93 dst_sel:DWORD dst_unused:UNUSED_PAD src0_sel:WORD_1
	v_cvt_f32_f16_e32 v164, v94
	v_cvt_f32_f16_sdwa v165, v94 dst_sel:DWORD dst_unused:UNUSED_PAD src0_sel:WORD_1
	v_cvt_f32_f16_e32 v166, v95
	v_cvt_f32_f16_sdwa v167, v95 dst_sel:DWORD dst_unused:UNUSED_PAD src0_sel:WORD_1
	v_cvt_f32_f16_e32 v168, v96
	v_cvt_f32_f16_sdwa v169, v96 dst_sel:DWORD dst_unused:UNUSED_PAD src0_sel:WORD_1
	v_cvt_f32_f16_e32 v170, v97
	v_cvt_f32_f16_sdwa v171, v97 dst_sel:DWORD dst_unused:UNUSED_PAD src0_sel:WORD_1
	v_cvt_f32_f16_e32 v172, v98
	v_cvt_f32_f16_sdwa v173, v98 dst_sel:DWORD dst_unused:UNUSED_PAD src0_sel:WORD_1
	v_cvt_f32_f16_e32 v174, v99
	v_cvt_f32_f16_sdwa v175, v99 dst_sel:DWORD dst_unused:UNUSED_PAD src0_sel:WORD_1
	v_pk_mul_f32 v[92:93], v[160:161], v[168:169]
	v_pk_mul_f32 v[94:95], v[162:163], v[170:171]
	v_pk_mul_f32 v[96:97], v[164:165], v[172:173]
	v_pk_mul_f32 v[98:99], v[166:167], v[174:175]
	v_cndmask_b32_e64 v92, 0, v92, s[4:5]
	v_cndmask_b32_e64 v93, 0, v93, s[4:5]
	v_cndmask_b32_e64 v94, 0, v94, s[4:5]
	v_cndmask_b32_e64 v95, 0, v95, s[4:5]
	v_cndmask_b32_e64 v96, 0, v96, s[4:5]
	v_cndmask_b32_e64 v97, 0, v97, s[4:5]
	v_cndmask_b32_e64 v98, 0, v98, s[4:5]
	v_cndmask_b32_e64 v99, 0, v99, s[4:5]
	v_cvt_f32_f16_e32 v184, v100
	v_cvt_f32_f16_sdwa v185, v100 dst_sel:DWORD dst_unused:UNUSED_PAD src0_sel:WORD_1
	v_cvt_f32_f16_e32 v186, v101
	v_cvt_f32_f16_sdwa v187, v101 dst_sel:DWORD dst_unused:UNUSED_PAD src0_sel:WORD_1
	v_cvt_f32_f16_e32 v188, v102
	v_cvt_f32_f16_sdwa v189, v102 dst_sel:DWORD dst_unused:UNUSED_PAD src0_sel:WORD_1
	v_cvt_f32_f16_e32 v190, v103
	v_cvt_f32_f16_sdwa v191, v103 dst_sel:DWORD dst_unused:UNUSED_PAD src0_sel:WORD_1
	v_pk_mul_f32 v[176:177], v[28:29], v[140:141]
	v_pk_mul_f32 v[178:179], v[30:31], v[142:143]
	v_pk_mul_f32 v[180:181], v[32:33], v[144:145]
	v_pk_mul_f32 v[182:183], v[34:35], v[146:147]
	v_pk_fma_f32 v[176:177], v[20:21], v[132:133], v[176:177]
	v_pk_fma_f32 v[178:179], v[22:23], v[134:135], v[178:179]
	v_pk_fma_f32 v[180:181], v[24:25], v[136:137], v[180:181]
	v_pk_fma_f32 v[182:183], v[26:27], v[138:139], v[182:183]
	v_pk_fma_f32 v[176:177], v[36:37], v[148:149], v[176:177]
	v_pk_fma_f32 v[178:179], v[38:39], v[150:151], v[178:179]
	v_pk_fma_f32 v[180:181], v[40:41], v[152:153], v[180:181]
	v_pk_fma_f32 v[182:183], v[42:43], v[154:155], v[182:183]
	v_pk_mul_f32 v[176:177], v[176:177], v[184:185]
	v_pk_mul_f32 v[178:179], v[178:179], v[186:187]
	v_pk_mul_f32 v[180:181], v[180:181], v[188:189]
	v_pk_mul_f32 v[182:183], v[182:183], v[190:191]
	v_cvt_pk_f16_f32 v192, v176, v177
	v_cvt_pk_f16_f32 v193, v178, v179
	v_cvt_pk_f16_f32 v194, v180, v181
	v_cvt_pk_f16_f32 v195, v182, v183
	global_store_dwordx4 v10, v[192:195], s[64:65] offset:512
	v_add_u32_e32 v10, 0x800, v10
	v_cvt_f32_f16_e32 v184, v104
	v_cvt_f32_f16_sdwa v185, v104 dst_sel:DWORD dst_unused:UNUSED_PAD src0_sel:WORD_1
	v_cvt_f32_f16_e32 v186, v105
	v_cvt_f32_f16_sdwa v187, v105 dst_sel:DWORD dst_unused:UNUSED_PAD src0_sel:WORD_1
	v_cvt_f32_f16_e32 v188, v106
	v_cvt_f32_f16_sdwa v189, v106 dst_sel:DWORD dst_unused:UNUSED_PAD src0_sel:WORD_1
	v_cvt_f32_f16_e32 v190, v107
	v_cvt_f32_f16_sdwa v191, v107 dst_sel:DWORD dst_unused:UNUSED_PAD src0_sel:WORD_1
	v_pk_mul_f32 v[176:177], v[36:37], v[140:141]
	v_pk_mul_f32 v[178:179], v[38:39], v[142:143]
	v_pk_mul_f32 v[180:181], v[40:41], v[144:145]
	v_pk_mul_f32 v[182:183], v[42:43], v[146:147]
	v_pk_fma_f32 v[176:177], v[28:29], v[132:133], v[176:177]
	v_pk_fma_f32 v[178:179], v[30:31], v[134:135], v[178:179]
	v_pk_fma_f32 v[180:181], v[32:33], v[136:137], v[180:181]
	v_pk_fma_f32 v[182:183], v[34:35], v[138:139], v[182:183]
	v_pk_fma_f32 v[176:177], v[44:45], v[148:149], v[176:177]
	v_pk_fma_f32 v[178:179], v[46:47], v[150:151], v[178:179]
	v_pk_fma_f32 v[180:181], v[48:49], v[152:153], v[180:181]
	v_pk_fma_f32 v[182:183], v[50:51], v[154:155], v[182:183]
	v_pk_mul_f32 v[176:177], v[176:177], v[184:185]
	v_pk_mul_f32 v[178:179], v[178:179], v[186:187]
	v_pk_mul_f32 v[180:181], v[180:181], v[188:189]
	v_pk_mul_f32 v[182:183], v[182:183], v[190:191]
	v_cvt_pk_f16_f32 v196, v176, v177
	v_cvt_pk_f16_f32 v197, v178, v179
	v_cvt_pk_f16_f32 v198, v180, v181
	v_cvt_pk_f16_f32 v199, v182, v183
	global_store_dwordx4 v10, v[196:199], s[64:65] offset:512
	v_add_u32_e32 v10, 0x800, v10
	v_cvt_f32_f16_e32 v184, v108
	v_cvt_f32_f16_sdwa v185, v108 dst_sel:DWORD dst_unused:UNUSED_PAD src0_sel:WORD_1
	v_cvt_f32_f16_e32 v186, v109
	v_cvt_f32_f16_sdwa v187, v109 dst_sel:DWORD dst_unused:UNUSED_PAD src0_sel:WORD_1
	v_cvt_f32_f16_e32 v188, v110
	v_cvt_f32_f16_sdwa v189, v110 dst_sel:DWORD dst_unused:UNUSED_PAD src0_sel:WORD_1
	v_cvt_f32_f16_e32 v190, v111
	v_cvt_f32_f16_sdwa v191, v111 dst_sel:DWORD dst_unused:UNUSED_PAD src0_sel:WORD_1
	v_pk_mul_f32 v[176:177], v[44:45], v[140:141]
	v_pk_mul_f32 v[178:179], v[46:47], v[142:143]
	v_pk_mul_f32 v[180:181], v[48:49], v[144:145]
	v_pk_mul_f32 v[182:183], v[50:51], v[146:147]
	v_pk_fma_f32 v[176:177], v[36:37], v[132:133], v[176:177]
	v_pk_fma_f32 v[178:179], v[38:39], v[134:135], v[178:179]
	v_pk_fma_f32 v[180:181], v[40:41], v[136:137], v[180:181]
	v_pk_fma_f32 v[182:183], v[42:43], v[138:139], v[182:183]
	v_pk_fma_f32 v[176:177], v[52:53], v[148:149], v[176:177]
	v_pk_fma_f32 v[178:179], v[54:55], v[150:151], v[178:179]
	v_pk_fma_f32 v[180:181], v[56:57], v[152:153], v[180:181]
	v_pk_fma_f32 v[182:183], v[58:59], v[154:155], v[182:183]
	v_pk_mul_f32 v[176:177], v[176:177], v[184:185]
	v_pk_mul_f32 v[178:179], v[178:179], v[186:187]
	v_pk_mul_f32 v[180:181], v[180:181], v[188:189]
	v_pk_mul_f32 v[182:183], v[182:183], v[190:191]
	v_cvt_pk_f16_f32 v192, v176, v177
	v_cvt_pk_f16_f32 v193, v178, v179
	v_cvt_pk_f16_f32 v194, v180, v181
	v_cvt_pk_f16_f32 v195, v182, v183
	global_store_dwordx4 v10, v[192:195], s[64:65] offset:512
	v_add_u32_e32 v10, 0x800, v10
	v_cvt_f32_f16_e32 v184, v112
	v_cvt_f32_f16_sdwa v185, v112 dst_sel:DWORD dst_unused:UNUSED_PAD src0_sel:WORD_1
	v_cvt_f32_f16_e32 v186, v113
	v_cvt_f32_f16_sdwa v187, v113 dst_sel:DWORD dst_unused:UNUSED_PAD src0_sel:WORD_1
	v_cvt_f32_f16_e32 v188, v114
	v_cvt_f32_f16_sdwa v189, v114 dst_sel:DWORD dst_unused:UNUSED_PAD src0_sel:WORD_1
	v_cvt_f32_f16_e32 v190, v115
	v_cvt_f32_f16_sdwa v191, v115 dst_sel:DWORD dst_unused:UNUSED_PAD src0_sel:WORD_1
	v_pk_mul_f32 v[176:177], v[52:53], v[140:141]
	v_pk_mul_f32 v[178:179], v[54:55], v[142:143]
	v_pk_mul_f32 v[180:181], v[56:57], v[144:145]
	v_pk_mul_f32 v[182:183], v[58:59], v[146:147]
	v_pk_fma_f32 v[176:177], v[44:45], v[132:133], v[176:177]
	v_pk_fma_f32 v[178:179], v[46:47], v[134:135], v[178:179]
	v_pk_fma_f32 v[180:181], v[48:49], v[136:137], v[180:181]
	v_pk_fma_f32 v[182:183], v[50:51], v[138:139], v[182:183]
	v_pk_fma_f32 v[176:177], v[60:61], v[148:149], v[176:177]
	v_pk_fma_f32 v[178:179], v[62:63], v[150:151], v[178:179]
	v_pk_fma_f32 v[180:181], v[64:65], v[152:153], v[180:181]
	v_pk_fma_f32 v[182:183], v[66:67], v[154:155], v[182:183]
	v_pk_mul_f32 v[176:177], v[176:177], v[184:185]
	v_pk_mul_f32 v[178:179], v[178:179], v[186:187]
	v_pk_mul_f32 v[180:181], v[180:181], v[188:189]
	v_pk_mul_f32 v[182:183], v[182:183], v[190:191]
	v_cvt_pk_f16_f32 v196, v176, v177
	v_cvt_pk_f16_f32 v197, v178, v179
	v_cvt_pk_f16_f32 v198, v180, v181
	v_cvt_pk_f16_f32 v199, v182, v183
	global_store_dwordx4 v10, v[196:199], s[64:65] offset:512
	v_add_u32_e32 v10, 0x800, v10
	v_cvt_f32_f16_e32 v184, v116
	v_cvt_f32_f16_sdwa v185, v116 dst_sel:DWORD dst_unused:UNUSED_PAD src0_sel:WORD_1
	v_cvt_f32_f16_e32 v186, v117
	v_cvt_f32_f16_sdwa v187, v117 dst_sel:DWORD dst_unused:UNUSED_PAD src0_sel:WORD_1
	v_cvt_f32_f16_e32 v188, v118
	v_cvt_f32_f16_sdwa v189, v118 dst_sel:DWORD dst_unused:UNUSED_PAD src0_sel:WORD_1
	v_cvt_f32_f16_e32 v190, v119
	v_cvt_f32_f16_sdwa v191, v119 dst_sel:DWORD dst_unused:UNUSED_PAD src0_sel:WORD_1
	v_pk_mul_f32 v[176:177], v[60:61], v[140:141]
	v_pk_mul_f32 v[178:179], v[62:63], v[142:143]
	v_pk_mul_f32 v[180:181], v[64:65], v[144:145]
	v_pk_mul_f32 v[182:183], v[66:67], v[146:147]
	v_pk_fma_f32 v[176:177], v[52:53], v[132:133], v[176:177]
	v_pk_fma_f32 v[178:179], v[54:55], v[134:135], v[178:179]
	v_pk_fma_f32 v[180:181], v[56:57], v[136:137], v[180:181]
	v_pk_fma_f32 v[182:183], v[58:59], v[138:139], v[182:183]
	v_pk_fma_f32 v[176:177], v[68:69], v[148:149], v[176:177]
	v_pk_fma_f32 v[178:179], v[70:71], v[150:151], v[178:179]
	v_pk_fma_f32 v[180:181], v[72:73], v[152:153], v[180:181]
	v_pk_fma_f32 v[182:183], v[74:75], v[154:155], v[182:183]
	v_pk_mul_f32 v[176:177], v[176:177], v[184:185]
	v_pk_mul_f32 v[178:179], v[178:179], v[186:187]
	v_pk_mul_f32 v[180:181], v[180:181], v[188:189]
	v_pk_mul_f32 v[182:183], v[182:183], v[190:191]
	v_cvt_pk_f16_f32 v192, v176, v177
	v_cvt_pk_f16_f32 v193, v178, v179
	v_cvt_pk_f16_f32 v194, v180, v181
	v_cvt_pk_f16_f32 v195, v182, v183
	global_store_dwordx4 v10, v[192:195], s[64:65] offset:512
	v_add_u32_e32 v10, 0x800, v10
	v_cvt_f32_f16_e32 v184, v120
	v_cvt_f32_f16_sdwa v185, v120 dst_sel:DWORD dst_unused:UNUSED_PAD src0_sel:WORD_1
	v_cvt_f32_f16_e32 v186, v121
	v_cvt_f32_f16_sdwa v187, v121 dst_sel:DWORD dst_unused:UNUSED_PAD src0_sel:WORD_1
	v_cvt_f32_f16_e32 v188, v122
	v_cvt_f32_f16_sdwa v189, v122 dst_sel:DWORD dst_unused:UNUSED_PAD src0_sel:WORD_1
	v_cvt_f32_f16_e32 v190, v123
	v_cvt_f32_f16_sdwa v191, v123 dst_sel:DWORD dst_unused:UNUSED_PAD src0_sel:WORD_1
	v_pk_mul_f32 v[176:177], v[68:69], v[140:141]
	v_pk_mul_f32 v[178:179], v[70:71], v[142:143]
	v_pk_mul_f32 v[180:181], v[72:73], v[144:145]
	v_pk_mul_f32 v[182:183], v[74:75], v[146:147]
	v_pk_fma_f32 v[176:177], v[60:61], v[132:133], v[176:177]
	v_pk_fma_f32 v[178:179], v[62:63], v[134:135], v[178:179]
	v_pk_fma_f32 v[180:181], v[64:65], v[136:137], v[180:181]
	v_pk_fma_f32 v[182:183], v[66:67], v[138:139], v[182:183]
	v_pk_fma_f32 v[176:177], v[76:77], v[148:149], v[176:177]
	v_pk_fma_f32 v[178:179], v[78:79], v[150:151], v[178:179]
	v_pk_fma_f32 v[180:181], v[80:81], v[152:153], v[180:181]
	v_pk_fma_f32 v[182:183], v[82:83], v[154:155], v[182:183]
	v_pk_mul_f32 v[176:177], v[176:177], v[184:185]
	v_pk_mul_f32 v[178:179], v[178:179], v[186:187]
	v_pk_mul_f32 v[180:181], v[180:181], v[188:189]
	v_pk_mul_f32 v[182:183], v[182:183], v[190:191]
	v_cvt_pk_f16_f32 v196, v176, v177
	v_cvt_pk_f16_f32 v197, v178, v179
	v_cvt_pk_f16_f32 v198, v180, v181
	v_cvt_pk_f16_f32 v199, v182, v183
	global_store_dwordx4 v10, v[196:199], s[64:65] offset:512
	v_add_u32_e32 v10, 0x800, v10
	v_cvt_f32_f16_e32 v184, v124
	v_cvt_f32_f16_sdwa v185, v124 dst_sel:DWORD dst_unused:UNUSED_PAD src0_sel:WORD_1
	v_cvt_f32_f16_e32 v186, v125
	v_cvt_f32_f16_sdwa v187, v125 dst_sel:DWORD dst_unused:UNUSED_PAD src0_sel:WORD_1
	v_cvt_f32_f16_e32 v188, v126
	v_cvt_f32_f16_sdwa v189, v126 dst_sel:DWORD dst_unused:UNUSED_PAD src0_sel:WORD_1
	v_cvt_f32_f16_e32 v190, v127
	v_cvt_f32_f16_sdwa v191, v127 dst_sel:DWORD dst_unused:UNUSED_PAD src0_sel:WORD_1
	v_pk_mul_f32 v[176:177], v[76:77], v[140:141]
	v_pk_mul_f32 v[178:179], v[78:79], v[142:143]
	v_pk_mul_f32 v[180:181], v[80:81], v[144:145]
	v_pk_mul_f32 v[182:183], v[82:83], v[146:147]
	v_pk_fma_f32 v[176:177], v[68:69], v[132:133], v[176:177]
	v_pk_fma_f32 v[178:179], v[70:71], v[134:135], v[178:179]
	v_pk_fma_f32 v[180:181], v[72:73], v[136:137], v[180:181]
	v_pk_fma_f32 v[182:183], v[74:75], v[138:139], v[182:183]
	v_pk_fma_f32 v[176:177], v[84:85], v[148:149], v[176:177]
	v_pk_fma_f32 v[178:179], v[86:87], v[150:151], v[178:179]
	v_pk_fma_f32 v[180:181], v[88:89], v[152:153], v[180:181]
	v_pk_fma_f32 v[182:183], v[90:91], v[154:155], v[182:183]
	v_pk_mul_f32 v[176:177], v[176:177], v[184:185]
	v_pk_mul_f32 v[178:179], v[178:179], v[186:187]
	v_pk_mul_f32 v[180:181], v[180:181], v[188:189]
	v_pk_mul_f32 v[182:183], v[182:183], v[190:191]
	v_cvt_pk_f16_f32 v192, v176, v177
	v_cvt_pk_f16_f32 v193, v178, v179
	v_cvt_pk_f16_f32 v194, v180, v181
	v_cvt_pk_f16_f32 v195, v182, v183
	global_store_dwordx4 v10, v[192:195], s[64:65] offset:512
	v_add_u32_e32 v10, 0x800, v10
	v_cvt_f32_f16_e32 v184, v128
	v_cvt_f32_f16_sdwa v185, v128 dst_sel:DWORD dst_unused:UNUSED_PAD src0_sel:WORD_1
	v_cvt_f32_f16_e32 v186, v129
	v_cvt_f32_f16_sdwa v187, v129 dst_sel:DWORD dst_unused:UNUSED_PAD src0_sel:WORD_1
	v_cvt_f32_f16_e32 v188, v130
	v_cvt_f32_f16_sdwa v189, v130 dst_sel:DWORD dst_unused:UNUSED_PAD src0_sel:WORD_1
	v_cvt_f32_f16_e32 v190, v131
	v_cvt_f32_f16_sdwa v191, v131 dst_sel:DWORD dst_unused:UNUSED_PAD src0_sel:WORD_1
	v_pk_mul_f32 v[176:177], v[84:85], v[140:141]
	v_pk_mul_f32 v[178:179], v[86:87], v[142:143]
	v_pk_mul_f32 v[180:181], v[88:89], v[144:145]
	v_pk_mul_f32 v[182:183], v[90:91], v[146:147]
	v_pk_fma_f32 v[176:177], v[76:77], v[132:133], v[176:177]
	v_pk_fma_f32 v[178:179], v[78:79], v[134:135], v[178:179]
	v_pk_fma_f32 v[180:181], v[80:81], v[136:137], v[180:181]
	v_pk_fma_f32 v[182:183], v[82:83], v[138:139], v[182:183]
	v_pk_fma_f32 v[176:177], v[92:93], v[148:149], v[176:177]
	v_pk_fma_f32 v[178:179], v[94:95], v[150:151], v[178:179]
	v_pk_fma_f32 v[180:181], v[96:97], v[152:153], v[180:181]
	v_pk_fma_f32 v[182:183], v[98:99], v[154:155], v[182:183]
	v_pk_mul_f32 v[176:177], v[176:177], v[184:185]
	v_pk_mul_f32 v[178:179], v[178:179], v[186:187]
	v_pk_mul_f32 v[180:181], v[180:181], v[188:189]
	v_pk_mul_f32 v[182:183], v[182:183], v[190:191]
	v_cvt_pk_f16_f32 v196, v176, v177
	v_cvt_pk_f16_f32 v197, v178, v179
	v_cvt_pk_f16_f32 v198, v180, v181
	v_cvt_pk_f16_f32 v199, v182, v183
	global_store_dwordx4 v10, v[196:199], s[64:65] offset:512
	s_mov_b64 s[2:3], 0

.LBB0_876:
	s_andn2_b64 vcc, exec, s[2:3]
	s_cbranch_vccnz .LBB0_911
	s_add_i32 s2, s7, 0xffffffb0
	s_lshr_b32 s3, s2, 5
	s_lshl_b32 s28, s2, 3
	s_lshl_b32 s4, s3, 11
	s_lshl_b32 s5, s7, 8
	s_mul_i32 s58, s3, 0x90000
	s_and_b32 s2, s28, 0xc0
	s_lshl_b32 s3, s3, 8
	s_and_b32 s5, s5, 0x700
	v_ashrrev_i32_e32 v1, 6, v212
	v_and_b32_e32 v22, 31, v212
	s_or_b32 s3, s2, s3
	s_mul_i32 s10, s3, 0x900
	v_lshl_or_b32 v2, v1, 5, v22
	s_or_b32 s3, s4, s5
	v_readlane_b32 s4, v255, 55
	s_lshl_b32 s4, s4, 6
	s_and_b32 s4, s4, 0x80
	s_add_i32 s3, s3, s4
	v_add_u32_e32 v148, s3, v2
	v_ashrrev_i32_e32 v149, 31, v148
	v_readlane_b32 s4, v255, 16
	v_lshlrev_b64 v[2:3], 9, v[148:149]
	v_readlane_b32 s5, v255, 17
	v_bfe_u32 v152, v212, 5, 1
	s_lshl_b32 s2, s2, 1
	v_lshl_add_u64 v[2:3], s[4:5], 0, v[2:3]
	s_mov_b32 s3, s59
	v_lshl_add_u64 v[2:3], v[2:3], 0, s[2:3]
	v_lshlrev_b32_e32 v210, 4, v152
	v_lshl_add_u64 v[14:15], v[2:3], 0, v[210:211]
	global_load_dwordx4 v[2:5], v[14:15], off
	global_load_dwordx4 v[6:9], v[14:15], off offset:32
	global_load_dwordx4 v[10:13], v[14:15], off offset:64
	s_nop 0
	global_load_dwordx4 v[14:17], v[14:15], off offset:96
	s_lshl_b64 s[4:5], s[58:59], 1
	v_readlane_b32 s12, v255, 18
	v_readlane_b32 s13, v255, 19
	s_add_u32 s3, s12, s4
	s_addc_u32 s9, s13, s5
	s_mov_b32 s11, s59
	s_add_u32 s12, s3, s2
	s_addc_u32 s13, s9, 0
	s_lshl_b64 s[10:11], s[10:11], 1
	v_readlane_b32 s14, v255, 20
	v_ashrrev_i32_e32 v142, 3, v212
	v_readlane_b32 s15, v255, 21
	s_add_u32 s10, s14, s10
	v_xor_b32_e32 v144, v223, v212
	v_ashrrev_i32_e32 v143, 31, v142
	v_lshlrev_b32_e32 v157, 4, v212
	s_addc_u32 s11, s15, s11
	v_lshlrev_b64 v[140:141], 9, v[142:143]
	v_readfirstlane_b32 s3, v1
	v_lshlrev_b32_e32 v1, 4, v144
	v_add_u32_e32 v154, 0xc000, v157
	v_mov_b64_e32 v[18:19], s[10:11]
	s_lshl_b32 s3, s3, 10
	s_waitcnt vmcnt(63) expcnt(7) lgkmcnt(15)
	s_barrier
	v_mad_i64_i32 v[18:19], s[10:11], v142, s39, v[18:19]
	s_mov_b32 m0, s3
	v_lshrrev_b32_e32 v23, 5, v212
	v_lshlrev_b32_e32 v159, 7, v22
	s_mov_b32 s22, s8
	s_mov_b32 s23, s8
	s_mov_b32 s9, s8
	s_mov_b32 s10, s8
	s_mov_b32 s11, s8
	s_mov_b32 s14, s8
	s_mov_b32 s15, s8
	s_mov_b32 s16, s8
	s_mov_b32 s17, s8
	s_mov_b32 s18, s8
	s_mov_b32 s19, s8
	s_mov_b32 s20, s8
	s_mov_b32 s21, s8
	s_waitcnt vmcnt(3)
	ds_write_b128 v157, v[2:5] offset:49152
	s_waitcnt vmcnt(2)
	ds_write_b128 v157, v[6:9] offset:57344
	s_waitcnt vmcnt(1)
	ds_write_b128 v154, v[10:13] offset:16384
	s_waitcnt vmcnt(0)
	ds_write_b128 v154, v[14:17] offset:24576
	v_lshl_add_u64 v[2:3], s[12:13], 0, v[140:141]
	v_and_b32_e32 v4, 0x70, v1
	v_mov_b32_e32 v5, v211
	v_lshl_add_u64 v[20:21], v[2:3], 0, v[4:5]
	v_lshl_add_u64 v[18:19], v[18:19], 0, v[4:5]
	global_load_lds_dwordx4 v[20:21], off
	s_add_i32 m0, s3, 0x2000
	v_lshl_add_u64 v[2:3], v[20:21], 0, s[42:43]
	global_load_lds_dwordx4 v[18:19], off
	s_add_i32 m0, s3, 0x4000
	v_bfe_u32 v1, v212, 1, 3
	global_load_lds_dwordx4 v[2:3], off
	v_lshl_add_u64 v[2:3], v[18:19], 0, s[66:67]
	s_add_i32 m0, s3, 0x6000
	s_mov_b32 s12, s8
	global_load_lds_dwordx4 v[2:3], off
	v_bitop3_b32 v2, v23, v1, 1 bitop3:0x6c
	v_lshlrev_b32_e32 v158, 4, v2
	v_or_b32_e32 v30, v159, v158
	s_waitcnt vmcnt(0)
	s_waitcnt vmcnt(0) lgkmcnt(0)
	s_barrier
	v_readlane_b32 vcc_lo, v255, 55
	s_cmp_eq_u32 vcc_lo, 0
	s_cbranch_scc1 .Lah_active
	s_cmp_lt_u32 s3, 0x1000
	s_cbranch_scc1 .Lah_active
	s_mov_b64 s[10:11], 0x10000
	v_lshl_add_u64 v[20:21], v[20:21], 0, s[10:11]
	v_lshl_add_u64 v[18:19], v[18:19], 0, s[76:77]
	s_mov_b32 s9, 0
	s_mov_b32 s10, 0x8000
.Lah_loop:
	s_cmp_lt_u32 s9, 34
	s_cbranch_scc0 .Lah_noissue
	s_add_i32 m0, s3, s10
	s_add_i32 s4, s10, 0x2000
	global_load_lds_dwordx4 v[20:21], off
	s_add_i32 m0, s3, s4
	s_nop 0
	global_load_lds_dwordx4 v[18:19], off
	v_lshl_add_u64 v[20:21], v[20:21], 0, s[42:43]
	v_lshl_add_u64 v[18:19], v[18:19], 0, s[66:67]
	s_add_i32 s10, s10, 0x4000
	s_cmp_eq_u32 s10, 0xc000
	s_cselect_b32 s10, 0, s10
.Lah_noissue:
	s_add_i32 s9, s9, 1
	s_waitcnt vmcnt(0)
	s_barrier
	s_cmp_lt_u32 s9, 36
	s_cbranch_scc1 .Lah_loop
	s_branch .LBB0_911
.Lah_active:
	ds_read_b128 v[22:25], v30
	ds_read_b128 v[26:29], v157 offset:49152
	s_mov_b32 s13, s8
	v_mov_b64_e32 v[110:111], s[22:23]
	v_mov_b64_e32 v[108:109], s[20:21]
	v_mov_b64_e32 v[106:107], s[18:19]
	v_mov_b64_e32 v[104:105], s[16:17]
	v_mov_b64_e32 v[102:103], s[14:15]
	v_mov_b64_e32 v[100:101], s[12:13]
	v_mov_b64_e32 v[98:99], s[10:11]
	v_mov_b64_e32 v[96:97], s[8:9]
	s_mov_b64 s[10:11], 0x10000
	v_lshl_add_u64 v[20:21], v[20:21], 0, s[10:11]
	s_waitcnt lgkmcnt(0)
	v_mfma_f32_32x32x16_f16 v[2:17], v[22:25], v[26:29], v[96:111]
	v_bitop3_b32 v22, v152, v1, 2 bitop3:0x36
	v_lshlrev_b32_e32 v160, 4, v22
	v_or_b32_e32 v31, v159, v160
	ds_read_b128 v[22:25], v31
	ds_read_b128 v[26:29], v157 offset:57344
	s_add_i32 m0, s3, 0x8000
	v_lshl_add_u64 v[18:19], v[18:19], 0, s[76:77]
	s_waitcnt lgkmcnt(0)
	v_mfma_f32_32x32x16_f16 v[2:17], v[22:25], v[26:29], v[2:17]
	v_bitop3_b32 v22, v152, v1, 4 bitop3:0x36
	v_lshlrev_b32_e32 v156, 4, v22
	v_or_b32_e32 v22, v159, v156
	ds_read_b128 v[22:25], v22
	ds_read_b128 v[26:29], v154 offset:16384
	v_bitop3_b32 v1, v152, v1, 6 bitop3:0x36
	v_lshlrev_b32_e32 v155, 4, v1
	v_or_b32_e32 v1, v159, v155
	s_waitcnt lgkmcnt(0)
	v_mfma_f32_32x32x16_f16 v[48:63], v[22:25], v[26:29], v[96:111]
	ds_read_b128 v[22:25], v1
	ds_read_b128 v[26:29], v154 offset:24576
	global_load_lds_dwordx4 v[20:21], off
	s_add_i32 m0, s3, 0xa000
	v_xor_b32_e32 v1, 32, v215
	global_load_lds_dwordx4 v[18:19], off
	ds_read_b128 v[18:21], v30 offset:4096
	ds_read_b128 v[136:139], v157 offset:49152
	s_waitcnt lgkmcnt(0)
	v_mfma_f32_32x32x16_f16 v[96:111], v[18:21], v[136:139], v[96:111]
	ds_read_b128 v[18:21], v31 offset:4096
	ds_read_b128 v[132:135], v157 offset:57344
	s_cmp_eq_u64 exec, 0
	v_mfma_f32_32x32x16_f16 v[48:63], v[22:25], v[26:29], v[48:63]
	v_and_b32_e32 v22, 64, v215
	v_add_u32_e32 v22, 64, v22
	v_cmp_lt_i32_e32 vcc, v1, v22
	s_nop 1
	v_cndmask_b32_e32 v1, v215, v1, vcc
	v_lshlrev_b32_e32 v153, 2, v1
	s_waitcnt lgkmcnt(0)
	v_mfma_f32_32x32x16_f16 v[96:111], v[18:21], v[132:135], v[96:111]
	v_max_f32_e32 v1, v3, v3
	v_max_f32_e32 v18, v2, v2
	v_max_f32_e32 v1, v18, v1
	v_max3_f32 v1, v1, v4, v5
	v_max3_f32 v1, v1, v6, v7
	v_max3_f32 v1, v1, v8, v9
	v_max3_f32 v1, v1, v10, v11
	v_max3_f32 v1, v1, v12, v13
	v_max3_f32 v1, v1, v14, v15
	v_max3_f32 v1, v1, v16, v17
	ds_bpermute_b32 v18, v153, v1
	s_cbranch_scc1 .LBB0_879
	s_waitcnt lgkmcnt(0)
	v_max_f32_e32 v18, v18, v18
	v_max_f32_e32 v1, v1, v1
	v_max_f32_e32 v18, v1, v18
	v_add_f32_e32 v169, 0, v18
	v_pk_add_f32 v[2:3], v[2:3], v[18:19] op_sel_hi:[1,0] neg_lo:[0,1] neg_hi:[0,1]
	v_pk_add_f32 v[4:5], v[4:5], v[18:19] op_sel_hi:[1,0] neg_lo:[0,1] neg_hi:[0,1]
	v_pk_add_f32 v[6:7], v[6:7], v[18:19] op_sel_hi:[1,0] neg_lo:[0,1] neg_hi:[0,1]
	v_pk_add_f32 v[8:9], v[8:9], v[18:19] op_sel_hi:[1,0] neg_lo:[0,1] neg_hi:[0,1]
	v_pk_add_f32 v[10:11], v[10:11], v[18:19] op_sel_hi:[1,0] neg_lo:[0,1] neg_hi:[0,1]
	v_pk_add_f32 v[12:13], v[12:13], v[18:19] op_sel_hi:[1,0] neg_lo:[0,1] neg_hi:[0,1]
	v_pk_add_f32 v[14:15], v[14:15], v[18:19] op_sel_hi:[1,0] neg_lo:[0,1] neg_hi:[0,1]
	v_pk_add_f32 v[16:17], v[16:17], v[18:19] op_sel_hi:[1,0] neg_lo:[0,1] neg_hi:[0,1]
	v_sub_f32_e32 v111, v111, v18
	v_sub_f32_e32 v110, v110, v18
	v_sub_f32_e32 v109, v109, v18
	v_sub_f32_e32 v108, v108, v18
	v_sub_f32_e32 v107, v107, v18
	v_sub_f32_e32 v106, v106, v18
	v_sub_f32_e32 v105, v105, v18
	v_sub_f32_e32 v104, v104, v18
	v_sub_f32_e32 v103, v103, v18
	v_sub_f32_e32 v102, v102, v18
	v_sub_f32_e32 v101, v101, v18
	v_sub_f32_e32 v100, v100, v18
	v_sub_f32_e32 v99, v99, v18
	v_sub_f32_e32 v98, v98, v18
	v_sub_f32_e32 v97, v97, v18
	v_sub_f32_e32 v96, v96, v18
	s_branch .LBB0_880
